# v18 plus one static s_setprio 1 for waves 4-7 per GEMM phase (7 GEMM loops)
# baseline (speedup 1.0000x reference)
;     __device__ bool next(int i, Unit& u) const { const int idx = i * G + c; if (idx >= 64) return false; u.kp = idx & 3; u.pn = (idx >> 2) & 7; u.pm = 192 + (idx >> 5); return true; }
; #define PG8_STAGE(bufoff, gbase, voff) do { _Pragma("unroll") for (int _i = 0; _i < 2; ++_i) \
;         __builtin_amdgcn_global_load_lds((const unsigned*)((const char*)(gbase) + (voff)[_i]), (LAS unsigned*)(lds + (bufoff) + ldsw + _i * 8192), 16, 0, 0); } while (0)
; #define PG8_WAIT_V(n) asm volatile("s_waitcnt vmcnt(" #n ")" ::: "memory")
; #define PG8_BAR __builtin_amdgcn_s_barrier()
; template <class Epi, class Sched = StaticOrder, bool ALIGN_EPI = true>
; __device__ __forceinline__ void gemm_phase(LAS unsigned char* lds, const Gemm g, const Sched& S, const Epi& E) {
;     ...
;     for (int i = 0; i < 2; ++i) { int R, C; stage_rc(tid * 16 + i * 8192, R, C); const int Rb = Epi::PERM ? ((R & ~31) + perm32(R & 31)) : R;
;         voffA[i] = (unsigned)(R * g.ld + C) * 2u; voffB[i] = (unsigned)(Rb * g.ld + C) * 2u; }
;     const size_t kstep = (size_t)(BK * 2);
;     const size_t hstep = (size_t)HALF * g.ld * 2;
;     const size_t tstep = 2 * hstep;
;     const unsigned ldsw = (unsigned)wid * 1024u;
;     const int aoff = lds_byte(wr * 64 + fr, fq * 8), boff = lds_byte(wc * 32 + fr, fq * 8);
;     ...
;     Unit cur, nxt; int ui = 0;
;     if (!S.next(0, cur)) return;
;     f32x4 acc[2][2][4][2];
; #pragma unroll
;     for (int a = 0; a < 2; ++a)
; #pragma unroll
;         for (int b = 0; b < 2; ++b)
; #pragma unroll
;             for (int m = 0; m < 4; ++m)
; #pragma unroll
;                 for (int n = 0; n < 2; ++n) acc[a][b][m][n] = (f32x4){0.f, 0.f, 0.f, 0.f};
;     bf16x8 At[4][2], B0[2][2], B1[2][2];
;     const char* cA = (const char*)g.A + (size_t)cur.pm * tstep + (size_t)cur.kp * K * 2; const char* cB = (const char*)g.Bt + (size_t)cur.pn * tstep + (size_t)cur.kp * K * 2;
;     PG8_STAGE(PG8_SB(0, 0), cB, voffB); PG8_STAGE(PG8_SB(0, 1), cB + hstep, voffB); PG8_STAGE(PG8_SA(0, 0), cA, voffA); PG8_STAGE(PG8_SA(0, 1), cA + hstep, voffA);
;     if (wr == 1) PG8_BAR;
;     PG8_WAIT_V(2); PG8_BAR;
;     PG8_STAGE(PG8_SB(1, 0), cB + kstep, voffB); PG8_STAGE(PG8_SA(1, 0), cA + kstep, voffA); PG8_STAGE(PG8_SB(1, 1), cB + hstep + kstep, voffB);
;     PG8_WAIT_V(6); PG8_BAR;
.LBB0_117:
	v_bfe_u32 v18, v1, 4, 2
	v_and_b32_e32 v19, 15, v1
	v_lshlrev_b32_e32 v20, 4, v18
	v_lshlrev_b32_e32 v1, 2, v1
	v_mov_b32_e32 v133, v0
	v_lshl_or_b32 v20, v19, 6, v20
	s_lshl_b32 s16, s21, 13
	v_and_b32_e32 v1, 32, v1
	v_lshl_add_u64 v[10:11], s[0:1], 0, v[132:133]
	v_mov_b32_e32 v131, v0
	v_bitop3_b32 v21, v20, s16, v1 bitop3:0xde
	s_lshl_b32 s16, s20, 5
	v_lshl_add_u64 v[12:13], s[0:1], 0, v[130:131]
	s_and_b32 s30, s16, 0x60
	s_add_i32 m0, s6, 0x18000
	v_lshl_add_u64 v[10:11], v[10:11], 0, s[34:35]
	v_lshl_add_u64 v[14:15], s[80:81], 0, v[132:133]
	s_lshl_b32 s13, s21, 6
	s_lshl_b32 s16, s30, 7
	s_waitcnt vmcnt(2)
	s_barrier
	global_load_lds_dwordx4 v[10:11], off
	v_lshl_add_u64 v[10:11], v[12:13], 0, s[34:35]
	s_add_i32 m0, s6, 0x1a000
	s_add_i32 s22, s6, 0x8000
	s_add_i32 s23, s6, 0xa000
	v_lshl_add_u64 v[16:17], s[80:81], 0, v[130:131]
	v_bitop3_b32 v1, v20, s16, v1 bitop3:0xde
	global_load_lds_dwordx4 v[10:11], off
	v_lshl_add_u64 v[10:11], v[14:15], 0, s[34:35]
	s_mov_b32 m0, s22
	s_add_u32 s16, s0, 0x80080
	global_load_lds_dwordx4 v[10:11], off
	v_lshl_add_u64 v[10:11], v[16:17], 0, s[34:35]
	s_mov_b32 m0, s23
	s_addc_u32 s17, s1, 0
	global_load_lds_dwordx4 v[10:11], off
	s_add_i32 m0, s6, 0x1c000
	v_lshl_add_u64 v[10:11], s[16:17], 0, v[132:133]
	global_load_lds_dwordx4 v[10:11], off
	v_lshl_add_u64 v[10:11], s[16:17], 0, v[130:131]
	s_add_i32 m0, s6, 0x1e000
	v_lshlrev_b32_e32 v7, 14, v7
	global_load_lds_dwordx4 v[10:11], off
	v_lshlrev_b32_e32 v2, 14, v2
	s_cmpk_lt_u32 s18, 0x100
	v_and_b32_e32 v7, 0x7fff8000, v7
	v_and_b32_e32 v2, 0x7fff8000, v2
	s_cselect_b64 s[20:21], -1, 0
	s_ashr_i32 s16, s13, 31
	v_lshl_add_u32 v6, v6, 11, v7
	v_lshl_add_u32 v2, v3, 11, v2
	s_waitcnt vmcnt(6)
	v_or_b32_e32 v10, s13, v19
	v_mov_b32_e32 v11, s16
	v_or_b32_e32 v6, v6, v8
	v_or_b32_e32 v2, v2, v4
	v_lshlrev_b64 v[134:135], 13, v[10:11]
	v_lshlrev_b32_e32 v10, 2, v18
	v_add_lshl_u32 v6, v6, v9, 1
	v_mov_b32_e32 v7, v0
	s_mov_b64 s[16:17], 0x80080
	v_add_lshl_u32 v2, v2, v5, 1
	v_mov_b32_e32 v3, v0
	v_lshl_add_u64 v[136:137], v[6:7], 0, s[16:17]
	v_lshl_add_u64 v[138:139], v[2:3], 0, s[16:17]
	s_mov_b32 s36, 0
	v_add_u32_e32 v142, 0, v21
	s_lshl_b32 s40, s30, 2
	v_lshlrev_b32_e32 v140, 2, v10
	s_barrier
	s_cmp_eq_u64 s[2:3], 0
	s_cbranch_scc1 .Lmy_pr_120
	s_setprio 1

;     __device__ bool next(int i, Unit& u) const { const int idx = i * G + c; if (idx >= 64) return false; u.kp = idx & 3; u.pn = (idx >> 2) & 7; u.pm = 192 + (idx >> 5); return true; }
; #define PG8_STAGE(bufoff, gbase, voff) do { _Pragma("unroll") for (int _i = 0; _i < 2; ++_i) \
;         __builtin_amdgcn_global_load_lds((const unsigned*)((const char*)(gbase) + (voff)[_i]), (LAS unsigned*)(lds + (bufoff) + ldsw + _i * 8192), 16, 0, 0); } while (0)
; #define PG8_WAIT_V(n) asm volatile("s_waitcnt vmcnt(" #n ")" ::: "memory")
; #define PG8_BAR __builtin_amdgcn_s_barrier()
; template <class Epi, class Sched = StaticOrder, bool ALIGN_EPI = true>
; __device__ __forceinline__ void gemm_phase(LAS unsigned char* lds, const Gemm g, const Sched& S, const Epi& E) {
;     ...
;     for (int i = 0; i < 2; ++i) { int R, C; stage_rc(tid * 16 + i * 8192, R, C); const int Rb = Epi::PERM ? ((R & ~31) + perm32(R & 31)) : R;
;         voffA[i] = (unsigned)(R * g.ld + C) * 2u; voffB[i] = (unsigned)(Rb * g.ld + C) * 2u; }
;     const size_t kstep = (size_t)(BK * 2);
;     const size_t hstep = (size_t)HALF * g.ld * 2;
;     const size_t tstep = 2 * hstep;
;     const unsigned ldsw = (unsigned)wid * 1024u;
;     const int aoff = lds_byte(wr * 64 + fr, fq * 8), boff = lds_byte(wc * 32 + fr, fq * 8);
;     ...
;     Unit cur, nxt; int ui = 0;
;     if (!S.next(0, cur)) return;
;     f32x4 acc[2][2][4][2];
; #pragma unroll
;     for (int a = 0; a < 2; ++a)
; #pragma unroll
;         for (int b = 0; b < 2; ++b)
; #pragma unroll
;             for (int m = 0; m < 4; ++m)
; #pragma unroll
;                 for (int n = 0; n < 2; ++n) acc[a][b][m][n] = (f32x4){0.f, 0.f, 0.f, 0.f};
;     bf16x8 At[4][2], B0[2][2], B1[2][2];
;     const char* cA = (const char*)g.A + (size_t)cur.pm * tstep + (size_t)cur.kp * K * 2; const char* cB = (const char*)g.Bt + (size_t)cur.pn * tstep + (size_t)cur.kp * K * 2;
;     PG8_STAGE(PG8_SB(0, 0), cB, voffB); PG8_STAGE(PG8_SB(0, 1), cB + hstep, voffB); PG8_STAGE(PG8_SA(0, 0), cA, voffA); PG8_STAGE(PG8_SA(0, 1), cA + hstep, voffA);
;     if (wr == 1) PG8_BAR;
;     PG8_WAIT_V(2); PG8_BAR;
;     PG8_STAGE(PG8_SB(1, 0), cB + kstep, voffB); PG8_STAGE(PG8_SA(1, 0), cA + kstep, voffA); PG8_STAGE(PG8_SB(1, 1), cB + hstep + kstep, voffB);
;     PG8_WAIT_V(6); PG8_BAR;
.LBB0_403:
	v_bfe_u32 v18, v1, 4, 2
	v_and_b32_e32 v19, 15, v1
	v_lshlrev_b32_e32 v20, 4, v18
	v_lshlrev_b32_e32 v1, 2, v1
	v_lshl_or_b32 v20, v19, 6, v20
	s_lshl_b32 s16, s20, 13
	v_and_b32_e32 v1, 32, v1
	v_bitop3_b32 v21, v20, s16, v1 bitop3:0xde
	s_lshl_b32 s16, s18, 5
	s_and_b32 s18, s16, 0x60
	s_add_i32 m0, s6, 0x18000
	v_lshl_add_u64 v[8:9], v[8:9], 0, s[34:35]
	s_lshl_b32 s30, s20, 6
	s_lshl_b32 s16, s18, 7
	s_waitcnt vmcnt(2)
	s_barrier
	global_load_lds_dwordx4 v[8:9], off
	v_lshl_add_u64 v[6:7], v[6:7], 0, s[34:35]
	s_add_i32 m0, s6, 0x1a000
	s_add_i32 s22, s6, 0x8000
	s_add_i32 s23, s6, 0xa000
	v_bitop3_b32 v1, v20, s16, v1 bitop3:0xde
	global_load_lds_dwordx4 v[6:7], off
	v_lshl_add_u64 v[2:3], v[2:3], 0, s[34:35]
	s_mov_b32 m0, s22
	s_add_u32 s16, s0, 0x160080
	global_load_lds_dwordx4 v[2:3], off
	v_lshl_add_u64 v[2:3], v[4:5], 0, s[34:35]
	s_mov_b32 m0, s23
	s_addc_u32 s17, s1, 0
	global_load_lds_dwordx4 v[2:3], off
	s_add_i32 m0, s6, 0x1c000
	v_lshl_add_u64 v[2:3], s[16:17], 0, v[132:133]
	global_load_lds_dwordx4 v[2:3], off
	v_lshl_add_u64 v[2:3], s[16:17], 0, v[130:131]
	s_add_i32 m0, s6, 0x1e000
	s_cmpk_lt_u32 s3, 0x100
	global_load_lds_dwordx4 v[2:3], off
	s_cselect_b64 s[20:21], -1, 0
	s_ashr_i32 s3, s30, 31
	v_or_b32_e32 v2, s30, v19
	v_mov_b32_e32 v3, s3
	s_movk_i32 s30, 0x1600
	v_lshlrev_b64 v[134:135], 13, v[2:3]
	v_lshrrev_b32_e32 v3, 1, v15
	v_mul_lo_u32 v4, v14, s30
	s_mov_b32 s3, 0x16000
	v_mad_u64_u32 v[4:5], s[16:17], v3, s3, v[4:5]
	v_or_b32_e32 v3, v4, v16
	v_add_lshl_u32 v4, v3, v17, 1
	v_mov_b32_e32 v5, v0
	s_mov_b64 s[36:37], 0x160080
	v_lshl_add_u64 v[136:137], v[4:5], 0, s[36:37]
	v_lshrrev_b32_e32 v3, 1, v10
	v_mul_lo_u32 v4, v11, s30
	v_mad_u64_u32 v[4:5], s[16:17], v3, s3, v[4:5]
	s_waitcnt vmcnt(6)
	v_or_b32_e32 v3, v4, v12
	v_lshlrev_b32_e32 v2, 2, v18
	v_add_lshl_u32 v4, v3, v13, 1
	v_mov_b32_e32 v5, v0
	v_lshl_add_u64 v[138:139], v[4:5], 0, s[36:37]
	s_mov_b32 s70, 0
	v_add_u32_e32 v142, 0, v21
	s_lshl_b32 s36, s18, 2
	v_lshlrev_b32_e32 v140, 2, v2
	s_mov_b64 s[42:43], s[46:47]
	s_barrier
	s_waitcnt vmcnt(0)
	s_cmp_eq_u64 s[2:3], 0
	s_cbranch_scc1 .Lmy_pr_406
	s_setprio 1
